# MLP-in (relu squared) epilogue stores marked streaming (nt) on top of the in-proj nt version
# baseline (speedup 1.0000x reference)
.LBB0_1340:
	v_lshl_add_u32 v142, s48, 8, v146
	v_ashrrev_i32_e32 v143, 31, v142
	v_lshlrev_b64 v[144:145], 14, v[142:143]
	ds_read_b32 v143, v148
	v_max_f32_e32 v122, v122, v122
	v_max_f32_e32 v122, 0, v122
	v_max_f32_e32 v123, v123, v123
	v_max_f32_e32 v124, v124, v124
	s_waitcnt lgkmcnt(0)
	v_mul_f32_e32 v122, v122, v143
	v_max_f32_e32 v123, 0, v123
	v_max_f32_e32 v124, 0, v124
	v_mul_f32_e32 v151, v122, v122
	v_max_f32_e32 v122, v127, v127
	v_mul_f32_e32 v123, v123, v143
	v_mul_f32_e32 v124, v124, v143
	v_lshl_or_b32 v140, s28, 8, v149
	v_max_f32_e32 v126, v126, v126
	v_max_f32_e32 v122, 0, v122
	v_mul_f32_e32 v127, v123, v123
	v_max_f32_e32 v123, v128, v128
	v_mul_f32_e32 v128, v124, v124
	v_max_f32_e32 v124, v129, v129
	v_max_f32_e32 v125, v125, v125
	v_ashrrev_i32_e32 v141, 31, v140
	v_max_f32_e32 v126, 0, v126
	v_mul_f32_e32 v122, v122, v143
	v_max_f32_e32 v123, 0, v123
	v_max_f32_e32 v124, 0, v124
	v_max_f32_e32 v125, 0, v125
	v_max_f32_e32 v114, v114, v114
	v_max_f32_e32 v115, v115, v115
	v_max_f32_e32 v116, v116, v116
	v_lshl_add_u64 v[152:153], s[18:19], 0, v[144:145]
	v_lshlrev_b64 v[144:145], 1, v[140:141]
	v_mul_f32_e32 v126, v126, v143
	v_mul_f32_e32 v122, v122, v122
	v_mul_f32_e32 v123, v123, v143
	v_mul_f32_e32 v124, v124, v143
	v_mul_f32_e32 v125, v125, v143
	v_max_f32_e32 v114, 0, v114
	v_max_f32_e32 v115, 0, v115
	v_max_f32_e32 v116, 0, v116
	v_lshl_add_u64 v[140:141], v[152:153], 0, v[144:145]
	v_mul_f32_e32 v126, v126, v126
	v_mul_f32_e32 v123, v123, v123
	v_mul_f32_e32 v124, v124, v124
	v_mul_f32_e32 v125, v125, v125
	v_cvt_pk_bf16_f32 v122, v126, v122
	v_mul_f32_e32 v114, v114, v143
	v_mul_f32_e32 v115, v115, v143
	v_mul_f32_e32 v116, v116, v143
	v_cvt_pk_bf16_f32 v123, v123, v124
	v_cvt_pk_bf16_f32 v124, v151, v127
	v_cvt_pk_bf16_f32 v125, v128, v125
	global_store_dwordx4 v[140:141], v[122:125], off nt
	v_max_f32_e32 v118, v118, v118
	v_max_f32_e32 v117, v117, v117
	v_mul_f32_e32 v122, v114, v114
	v_max_f32_e32 v114, v119, v119
	v_mul_f32_e32 v119, v115, v115
	v_max_f32_e32 v115, v120, v120
	v_mul_f32_e32 v120, v116, v116
	v_max_f32_e32 v116, v121, v121
	v_max_f32_e32 v114, 0, v114
	v_max_f32_e32 v115, 0, v115
	v_max_f32_e32 v116, 0, v116
	v_max_f32_e32 v118, 0, v118
	v_mul_f32_e32 v114, v114, v143
	v_mul_f32_e32 v115, v115, v143
	v_mul_f32_e32 v116, v116, v143
	v_max_f32_e32 v117, 0, v117
	v_mul_f32_e32 v118, v118, v143
	v_mul_f32_e32 v114, v114, v114
	v_mul_f32_e32 v115, v115, v115
	v_mul_f32_e32 v117, v117, v143
	v_mul_f32_e32 v116, v116, v116
	v_mul_f32_e32 v118, v118, v118
	v_mul_f32_e32 v117, v117, v117
	v_cvt_pk_bf16_f32 v114, v118, v114
	v_cvt_pk_bf16_f32 v115, v115, v116
	v_cvt_pk_bf16_f32 v116, v122, v119
	v_cvt_pk_bf16_f32 v117, v120, v117
	global_store_dwordx4 v[140:141], v[114:117], off offset:256 nt
	ds_read_b32 v116, v148 offset:64
	v_max_f32_e32 v106, v106, v106
	v_max_f32_e32 v106, 0, v106
	v_max_f32_e32 v107, v107, v107
	v_max_f32_e32 v108, v108, v108
	s_waitcnt lgkmcnt(0)
	v_mul_f32_e32 v106, v106, v116
	v_max_f32_e32 v107, 0, v107
	v_max_f32_e32 v108, 0, v108
	v_or_b32_e32 v114, 16, v142
	v_mul_f32_e32 v117, v106, v106
	v_max_f32_e32 v106, v111, v111
	v_mul_f32_e32 v107, v107, v116
	v_mul_f32_e32 v108, v108, v116
	v_ashrrev_i32_e32 v115, 31, v114
	v_max_f32_e32 v110, v110, v110
	v_max_f32_e32 v106, 0, v106
	v_mul_f32_e32 v111, v107, v107
	v_max_f32_e32 v107, v112, v112
	v_mul_f32_e32 v112, v108, v108
	v_max_f32_e32 v108, v113, v113
	v_max_f32_e32 v109, v109, v109
	v_lshlrev_b64 v[114:115], 14, v[114:115]
	v_max_f32_e32 v110, 0, v110
	v_mul_f32_e32 v106, v106, v116
	v_max_f32_e32 v107, 0, v107
	v_max_f32_e32 v108, 0, v108
	v_max_f32_e32 v109, 0, v109
	v_max_f32_e32 v98, v98, v98
	v_max_f32_e32 v99, v99, v99
	v_max_f32_e32 v100, v100, v100
	v_lshl_add_u64 v[114:115], s[18:19], 0, v[114:115]
	v_mul_f32_e32 v110, v110, v116
	v_mul_f32_e32 v106, v106, v106
	v_mul_f32_e32 v107, v107, v116
	v_mul_f32_e32 v108, v108, v116
	v_mul_f32_e32 v109, v109, v116
	v_max_f32_e32 v98, 0, v98
	v_max_f32_e32 v99, 0, v99
	v_max_f32_e32 v100, 0, v100
	v_lshl_add_u64 v[114:115], v[114:115], 0, v[144:145]
	v_mul_f32_e32 v110, v110, v110
	v_mul_f32_e32 v107, v107, v107
	v_mul_f32_e32 v108, v108, v108
	v_mul_f32_e32 v109, v109, v109
	v_cvt_pk_bf16_f32 v106, v110, v106
	v_mul_f32_e32 v98, v98, v116
	v_mul_f32_e32 v99, v99, v116
	v_mul_f32_e32 v100, v100, v116
	v_cvt_pk_bf16_f32 v107, v107, v108
	v_cvt_pk_bf16_f32 v108, v117, v111
	v_cvt_pk_bf16_f32 v109, v112, v109
	global_store_dwordx4 v[114:115], v[106:109], off nt
	v_max_f32_e32 v102, v102, v102
	v_max_f32_e32 v101, v101, v101
	v_mul_f32_e32 v106, v98, v98
	v_max_f32_e32 v98, v103, v103
	v_mul_f32_e32 v103, v99, v99
	v_max_f32_e32 v99, v104, v104
	v_mul_f32_e32 v104, v100, v100
	v_max_f32_e32 v100, v105, v105
	v_max_f32_e32 v98, 0, v98
	v_max_f32_e32 v99, 0, v99
	v_max_f32_e32 v100, 0, v100
	v_max_f32_e32 v102, 0, v102
	v_mul_f32_e32 v98, v98, v116
	v_mul_f32_e32 v99, v99, v116
	v_mul_f32_e32 v100, v100, v116
	v_max_f32_e32 v101, 0, v101
	v_mul_f32_e32 v102, v102, v116
	v_mul_f32_e32 v98, v98, v98
	v_mul_f32_e32 v99, v99, v99
	v_mul_f32_e32 v101, v101, v116
	v_mul_f32_e32 v100, v100, v100
	v_mul_f32_e32 v102, v102, v102
	v_mul_f32_e32 v101, v101, v101
	v_cvt_pk_bf16_f32 v98, v102, v98
	v_cvt_pk_bf16_f32 v99, v99, v100
	v_cvt_pk_bf16_f32 v100, v106, v103
	v_cvt_pk_bf16_f32 v101, v104, v101
	global_store_dwordx4 v[114:115], v[98:101], off offset:256 nt
	ds_read_b32 v100, v148 offset:128
	v_max_f32_e32 v90, v90, v90
	v_max_f32_e32 v90, 0, v90
	v_max_f32_e32 v91, v91, v91
	v_max_f32_e32 v92, v92, v92
	s_waitcnt lgkmcnt(0)
	v_mul_f32_e32 v90, v90, v100
	v_max_f32_e32 v91, 0, v91
	v_max_f32_e32 v92, 0, v92
	v_or_b32_e32 v98, 32, v142
	v_mul_f32_e32 v101, v90, v90
	v_max_f32_e32 v90, v95, v95
	v_mul_f32_e32 v91, v91, v100
	v_mul_f32_e32 v92, v92, v100
	v_ashrrev_i32_e32 v99, 31, v98
	v_max_f32_e32 v94, v94, v94
	v_max_f32_e32 v90, 0, v90
	v_mul_f32_e32 v95, v91, v91
	v_max_f32_e32 v91, v96, v96
	v_mul_f32_e32 v96, v92, v92
	v_max_f32_e32 v92, v97, v97
	v_max_f32_e32 v93, v93, v93
	v_lshlrev_b64 v[98:99], 14, v[98:99]
	v_max_f32_e32 v94, 0, v94
	v_mul_f32_e32 v90, v90, v100
	v_max_f32_e32 v91, 0, v91
	v_max_f32_e32 v92, 0, v92
	v_max_f32_e32 v93, 0, v93
	v_max_f32_e32 v82, v82, v82
	v_max_f32_e32 v83, v83, v83
	v_max_f32_e32 v84, v84, v84
	v_lshl_add_u64 v[98:99], s[18:19], 0, v[98:99]
	v_mul_f32_e32 v94, v94, v100
	v_mul_f32_e32 v90, v90, v90
	v_mul_f32_e32 v91, v91, v100
	v_mul_f32_e32 v92, v92, v100
	v_mul_f32_e32 v93, v93, v100
	v_max_f32_e32 v82, 0, v82
	v_max_f32_e32 v83, 0, v83
	v_max_f32_e32 v84, 0, v84
	v_lshl_add_u64 v[98:99], v[98:99], 0, v[144:145]
	v_mul_f32_e32 v94, v94, v94
	v_mul_f32_e32 v91, v91, v91
	v_mul_f32_e32 v92, v92, v92
	v_mul_f32_e32 v93, v93, v93
	v_cvt_pk_bf16_f32 v90, v94, v90
	v_mul_f32_e32 v82, v82, v100
	v_mul_f32_e32 v83, v83, v100
	v_mul_f32_e32 v84, v84, v100
	v_cvt_pk_bf16_f32 v91, v91, v92
	v_cvt_pk_bf16_f32 v92, v101, v95
	v_cvt_pk_bf16_f32 v93, v96, v93
	global_store_dwordx4 v[98:99], v[90:93], off nt
	v_max_f32_e32 v86, v86, v86
	v_max_f32_e32 v85, v85, v85
	v_mul_f32_e32 v90, v82, v82
	v_max_f32_e32 v82, v87, v87
	v_mul_f32_e32 v87, v83, v83
	v_max_f32_e32 v83, v88, v88
	v_mul_f32_e32 v88, v84, v84
	v_max_f32_e32 v84, v89, v89
	v_max_f32_e32 v82, 0, v82
	v_max_f32_e32 v83, 0, v83
	v_max_f32_e32 v84, 0, v84
	v_max_f32_e32 v86, 0, v86
	v_mul_f32_e32 v82, v82, v100
	v_mul_f32_e32 v83, v83, v100
	v_mul_f32_e32 v84, v84, v100
	v_max_f32_e32 v85, 0, v85
	v_mul_f32_e32 v86, v86, v100
	v_mul_f32_e32 v82, v82, v82
	v_mul_f32_e32 v83, v83, v83
	v_mul_f32_e32 v85, v85, v100
	v_mul_f32_e32 v84, v84, v84
	v_mul_f32_e32 v86, v86, v86
	v_mul_f32_e32 v85, v85, v85
	v_cvt_pk_bf16_f32 v82, v86, v82
	v_cvt_pk_bf16_f32 v83, v83, v84
	v_cvt_pk_bf16_f32 v84, v90, v87
	v_cvt_pk_bf16_f32 v85, v88, v85
	global_store_dwordx4 v[98:99], v[82:85], off offset:256 nt
	ds_read_b32 v84, v148 offset:192
	v_max_f32_e32 v74, v74, v74
	v_max_f32_e32 v74, 0, v74
	v_max_f32_e32 v75, v75, v75
	v_max_f32_e32 v76, v76, v76
	s_waitcnt lgkmcnt(0)
	v_mul_f32_e32 v74, v74, v84
	v_max_f32_e32 v75, 0, v75
	v_max_f32_e32 v76, 0, v76
	v_or_b32_e32 v82, 48, v142
	v_mul_f32_e32 v85, v74, v74
	v_max_f32_e32 v74, v79, v79
	v_mul_f32_e32 v75, v75, v84
	v_mul_f32_e32 v76, v76, v84
	v_ashrrev_i32_e32 v83, 31, v82
	v_max_f32_e32 v78, v78, v78
	v_max_f32_e32 v74, 0, v74
	v_mul_f32_e32 v79, v75, v75
	v_max_f32_e32 v75, v80, v80
	v_mul_f32_e32 v80, v76, v76
	v_max_f32_e32 v76, v81, v81
	v_max_f32_e32 v77, v77, v77
	v_lshlrev_b64 v[82:83], 14, v[82:83]
	v_max_f32_e32 v78, 0, v78
	v_mul_f32_e32 v74, v74, v84
	v_max_f32_e32 v75, 0, v75
	v_max_f32_e32 v76, 0, v76
	v_max_f32_e32 v77, 0, v77
	v_max_f32_e32 v66, v66, v66
	v_max_f32_e32 v67, v67, v67
	v_max_f32_e32 v68, v68, v68
	v_lshl_add_u64 v[82:83], s[18:19], 0, v[82:83]
	v_mul_f32_e32 v78, v78, v84
	v_mul_f32_e32 v74, v74, v74
	v_mul_f32_e32 v75, v75, v84
	v_mul_f32_e32 v76, v76, v84
	v_mul_f32_e32 v77, v77, v84
	v_max_f32_e32 v66, 0, v66
	v_max_f32_e32 v67, 0, v67
	v_max_f32_e32 v68, 0, v68
	v_lshl_add_u64 v[82:83], v[82:83], 0, v[144:145]
	v_mul_f32_e32 v78, v78, v78
	v_mul_f32_e32 v75, v75, v75
	v_mul_f32_e32 v76, v76, v76
	v_mul_f32_e32 v77, v77, v77
	v_cvt_pk_bf16_f32 v74, v78, v74
	v_mul_f32_e32 v66, v66, v84
	v_mul_f32_e32 v67, v67, v84
	v_mul_f32_e32 v68, v68, v84
	v_cvt_pk_bf16_f32 v75, v75, v76
	v_cvt_pk_bf16_f32 v76, v85, v79
	v_cvt_pk_bf16_f32 v77, v80, v77
	global_store_dwordx4 v[82:83], v[74:77], off nt
	v_max_f32_e32 v70, v70, v70
	v_max_f32_e32 v69, v69, v69
	v_mul_f32_e32 v74, v66, v66
	v_max_f32_e32 v66, v71, v71
	v_mul_f32_e32 v71, v67, v67
	v_max_f32_e32 v67, v72, v72
	v_mul_f32_e32 v72, v68, v68
	v_max_f32_e32 v68, v73, v73
	v_max_f32_e32 v66, 0, v66
	v_max_f32_e32 v67, 0, v67
	v_max_f32_e32 v68, 0, v68
	v_max_f32_e32 v70, 0, v70
	v_mul_f32_e32 v66, v66, v84
	v_mul_f32_e32 v67, v67, v84
	v_mul_f32_e32 v68, v68, v84
	v_max_f32_e32 v69, 0, v69
	v_mul_f32_e32 v70, v70, v84
	v_mul_f32_e32 v66, v66, v66
	v_mul_f32_e32 v67, v67, v67
	v_mul_f32_e32 v69, v69, v84
	v_mul_f32_e32 v68, v68, v68
	v_mul_f32_e32 v70, v70, v70
	v_mul_f32_e32 v69, v69, v69
	v_cvt_pk_bf16_f32 v66, v70, v66
	v_cvt_pk_bf16_f32 v67, v67, v68
	v_cvt_pk_bf16_f32 v68, v74, v71
	v_cvt_pk_bf16_f32 v69, v72, v69
	global_store_dwordx4 v[82:83], v[66:69], off offset:256 nt
	ds_read_b32 v68, v148 offset:512
	v_max_f32_e32 v58, v58, v58
	v_max_f32_e32 v58, 0, v58
	v_max_f32_e32 v59, v59, v59
	v_max_f32_e32 v60, v60, v60
	s_waitcnt lgkmcnt(0)
	v_mul_f32_e32 v58, v58, v68
	v_max_f32_e32 v59, 0, v59
	v_max_f32_e32 v60, 0, v60
	v_max_f32_e32 v62, v62, v62
	v_mul_f32_e32 v69, v58, v58
	v_max_f32_e32 v58, v63, v63
	v_mul_f32_e32 v59, v59, v68
	v_mul_f32_e32 v60, v60, v68
	v_max_f32_e32 v62, 0, v62
	v_max_f32_e32 v58, 0, v58
	v_mul_f32_e32 v63, v59, v59
	v_max_f32_e32 v59, v64, v64
	v_mul_f32_e32 v64, v60, v60
	v_max_f32_e32 v60, v65, v65
	s_mov_b64 s[4:5], 0x200000
	v_mul_f32_e32 v62, v62, v68
	v_mul_f32_e32 v58, v58, v68
	v_max_f32_e32 v59, 0, v59
	v_max_f32_e32 v60, 0, v60
	v_max_f32_e32 v61, v61, v61
	v_lshl_add_u64 v[66:67], v[140:141], 0, s[4:5]
	v_mul_f32_e32 v62, v62, v62
	v_mul_f32_e32 v58, v58, v58
	v_mul_f32_e32 v59, v59, v68
	v_mul_f32_e32 v60, v60, v68
	v_max_f32_e32 v61, 0, v61
	s_mov_b32 s4, 0x200000
	v_max_f32_e32 v50, v50, v50
	v_max_f32_e32 v51, v51, v51
	v_max_f32_e32 v52, v52, v52
	v_mul_f32_e32 v59, v59, v59
	v_mul_f32_e32 v61, v61, v68
	v_mul_f32_e32 v60, v60, v60
	v_cvt_pk_bf16_f32 v58, v62, v58
	v_add_co_u32_e32 v62, vcc, s4, v140
	v_max_f32_e32 v50, 0, v50
	v_max_f32_e32 v51, 0, v51
	v_max_f32_e32 v52, 0, v52
	v_mul_f32_e32 v61, v61, v61
	v_cvt_pk_bf16_f32 v59, v59, v60
	v_cvt_pk_bf16_f32 v60, v69, v63
	v_addc_co_u32_e32 v63, vcc, 0, v141, vcc
	v_mul_f32_e32 v50, v50, v68
	v_mul_f32_e32 v51, v51, v68
	v_mul_f32_e32 v52, v52, v68
	v_cvt_pk_bf16_f32 v61, v64, v61
	global_store_dwordx4 v[62:63], v[58:61], off nt
	v_max_f32_e32 v54, v54, v54
	v_max_f32_e32 v53, v53, v53
	v_mul_f32_e32 v58, v50, v50
	v_max_f32_e32 v50, v55, v55
	v_mul_f32_e32 v55, v51, v51
	v_max_f32_e32 v51, v56, v56
	v_mul_f32_e32 v56, v52, v52
	v_max_f32_e32 v52, v57, v57
	v_max_f32_e32 v50, 0, v50
	v_max_f32_e32 v51, 0, v51
	v_max_f32_e32 v52, 0, v52
	v_max_f32_e32 v54, 0, v54
	v_mul_f32_e32 v50, v50, v68
	v_mul_f32_e32 v51, v51, v68
	v_mul_f32_e32 v52, v52, v68
	v_max_f32_e32 v53, 0, v53
	v_mul_f32_e32 v54, v54, v68
	v_mul_f32_e32 v50, v50, v50
	v_mul_f32_e32 v51, v51, v51
	v_mul_f32_e32 v53, v53, v68
	v_mul_f32_e32 v52, v52, v52
	v_mul_f32_e32 v54, v54, v54
	v_mul_f32_e32 v53, v53, v53
	v_cvt_pk_bf16_f32 v50, v54, v50
	v_cvt_pk_bf16_f32 v51, v51, v52
	v_cvt_pk_bf16_f32 v52, v58, v55
	v_cvt_pk_bf16_f32 v53, v56, v53
	global_store_dwordx4 v[66:67], v[50:53], off offset:256 nt
	ds_read_b32 v52, v148 offset:576
	v_max_f32_e32 v42, v42, v42
	v_max_f32_e32 v42, 0, v42
	v_max_f32_e32 v43, v43, v43
	v_max_f32_e32 v44, v44, v44
	s_waitcnt lgkmcnt(0)
	v_mul_f32_e32 v42, v42, v52
	v_max_f32_e32 v43, 0, v43
	v_max_f32_e32 v44, 0, v44
	v_max_f32_e32 v46, v46, v46
	v_mul_f32_e32 v53, v42, v42
	v_max_f32_e32 v42, v47, v47
	v_mul_f32_e32 v43, v43, v52
	v_mul_f32_e32 v44, v44, v52
	v_max_f32_e32 v46, 0, v46
	v_max_f32_e32 v42, 0, v42
	v_mul_f32_e32 v47, v43, v43
	v_max_f32_e32 v43, v48, v48
	v_mul_f32_e32 v48, v44, v44
	v_max_f32_e32 v44, v49, v49
	s_mov_b64 s[4:5], 0x240000
	v_mul_f32_e32 v46, v46, v52
	v_mul_f32_e32 v42, v42, v52
	v_max_f32_e32 v43, 0, v43
	v_max_f32_e32 v44, 0, v44
	v_max_f32_e32 v45, v45, v45
	v_lshl_add_u64 v[50:51], v[140:141], 0, s[4:5]
	v_mul_f32_e32 v46, v46, v46
	v_mul_f32_e32 v42, v42, v42
	v_mul_f32_e32 v43, v43, v52
	v_mul_f32_e32 v44, v44, v52
	v_max_f32_e32 v45, 0, v45
	s_mov_b32 s4, 0x240000
	v_max_f32_e32 v34, v34, v34
	v_max_f32_e32 v35, v35, v35
	v_max_f32_e32 v36, v36, v36
	v_mul_f32_e32 v43, v43, v43
	v_mul_f32_e32 v45, v45, v52
	v_mul_f32_e32 v44, v44, v44
	v_cvt_pk_bf16_f32 v42, v46, v42
	v_add_co_u32_e32 v46, vcc, s4, v140
	v_max_f32_e32 v34, 0, v34
	v_max_f32_e32 v35, 0, v35
	v_max_f32_e32 v36, 0, v36
	v_mul_f32_e32 v45, v45, v45
	v_cvt_pk_bf16_f32 v43, v43, v44
	v_cvt_pk_bf16_f32 v44, v53, v47
	v_addc_co_u32_e32 v47, vcc, 0, v141, vcc
	v_mul_f32_e32 v34, v34, v52
	v_mul_f32_e32 v35, v35, v52
	v_mul_f32_e32 v36, v36, v52
	v_cvt_pk_bf16_f32 v45, v48, v45
	global_store_dwordx4 v[46:47], v[42:45], off nt
	v_max_f32_e32 v38, v38, v38
	v_max_f32_e32 v37, v37, v37
	v_mul_f32_e32 v42, v34, v34
	v_max_f32_e32 v34, v39, v39
	v_mul_f32_e32 v39, v35, v35
	v_max_f32_e32 v35, v40, v40
	v_mul_f32_e32 v40, v36, v36
	v_max_f32_e32 v36, v41, v41
	v_max_f32_e32 v34, 0, v34
	v_max_f32_e32 v35, 0, v35
	v_max_f32_e32 v36, 0, v36
	v_max_f32_e32 v38, 0, v38
	v_mul_f32_e32 v34, v34, v52
	v_mul_f32_e32 v35, v35, v52
	v_mul_f32_e32 v36, v36, v52
	v_max_f32_e32 v37, 0, v37
	v_mul_f32_e32 v38, v38, v52
	v_mul_f32_e32 v34, v34, v34
	v_mul_f32_e32 v35, v35, v35
	v_mul_f32_e32 v37, v37, v52
	v_mul_f32_e32 v36, v36, v36
	v_mul_f32_e32 v38, v38, v38
	v_mul_f32_e32 v37, v37, v37
	v_cvt_pk_bf16_f32 v34, v38, v34
	v_cvt_pk_bf16_f32 v35, v35, v36
	v_cvt_pk_bf16_f32 v36, v42, v39
	v_cvt_pk_bf16_f32 v37, v40, v37
	global_store_dwordx4 v[50:51], v[34:37], off offset:256 nt
	ds_read_b32 v36, v148 offset:640
	v_max_f32_e32 v26, v26, v26
	v_max_f32_e32 v26, 0, v26
	v_max_f32_e32 v27, v27, v27
	v_max_f32_e32 v28, v28, v28
	s_waitcnt lgkmcnt(0)
	v_mul_f32_e32 v26, v26, v36
	v_max_f32_e32 v27, 0, v27
	v_max_f32_e32 v28, 0, v28
	v_max_f32_e32 v30, v30, v30
	v_mul_f32_e32 v37, v26, v26
	v_max_f32_e32 v26, v31, v31
	v_mul_f32_e32 v27, v27, v36
	v_mul_f32_e32 v28, v28, v36
	v_max_f32_e32 v30, 0, v30
	v_max_f32_e32 v26, 0, v26
	v_mul_f32_e32 v31, v27, v27
	v_max_f32_e32 v27, v32, v32
	v_mul_f32_e32 v32, v28, v28
	v_max_f32_e32 v28, v33, v33
	s_mov_b64 s[4:5], 0x280000
	v_mul_f32_e32 v30, v30, v36
	v_mul_f32_e32 v26, v26, v36
	v_max_f32_e32 v27, 0, v27
	v_max_f32_e32 v28, 0, v28
	v_max_f32_e32 v29, v29, v29
	v_lshl_add_u64 v[34:35], v[140:141], 0, s[4:5]
	v_mul_f32_e32 v30, v30, v30
	v_mul_f32_e32 v26, v26, v26
	v_mul_f32_e32 v27, v27, v36
	v_mul_f32_e32 v28, v28, v36
	v_max_f32_e32 v29, 0, v29
	s_mov_b32 s4, 0x280000
	v_max_f32_e32 v18, v18, v18
	v_max_f32_e32 v19, v19, v19
	v_max_f32_e32 v20, v20, v20
	v_mul_f32_e32 v27, v27, v27
	v_mul_f32_e32 v29, v29, v36
	v_mul_f32_e32 v28, v28, v28
	v_cvt_pk_bf16_f32 v26, v30, v26
	v_add_co_u32_e32 v30, vcc, s4, v140
	v_max_f32_e32 v18, 0, v18
	v_max_f32_e32 v19, 0, v19
	v_max_f32_e32 v20, 0, v20
	v_mul_f32_e32 v29, v29, v29
	v_cvt_pk_bf16_f32 v27, v27, v28
	v_cvt_pk_bf16_f32 v28, v37, v31
	v_addc_co_u32_e32 v31, vcc, 0, v141, vcc
	v_mul_f32_e32 v18, v18, v36
	v_mul_f32_e32 v19, v19, v36
	v_mul_f32_e32 v20, v20, v36
	v_cvt_pk_bf16_f32 v29, v32, v29
	global_store_dwordx4 v[30:31], v[26:29], off nt
	v_max_f32_e32 v22, v22, v22
	v_max_f32_e32 v21, v21, v21
	v_mul_f32_e32 v26, v18, v18
	v_max_f32_e32 v18, v23, v23
	v_mul_f32_e32 v23, v19, v19
	v_max_f32_e32 v19, v24, v24
	v_mul_f32_e32 v24, v20, v20
	v_max_f32_e32 v20, v25, v25
	v_max_f32_e32 v18, 0, v18
	v_max_f32_e32 v19, 0, v19
	v_max_f32_e32 v20, 0, v20
	v_max_f32_e32 v22, 0, v22
	v_mul_f32_e32 v18, v18, v36
	v_mul_f32_e32 v19, v19, v36
	v_mul_f32_e32 v20, v20, v36
	v_max_f32_e32 v21, 0, v21
	v_mul_f32_e32 v22, v22, v36
	v_mul_f32_e32 v18, v18, v18
	v_mul_f32_e32 v19, v19, v19
	v_mul_f32_e32 v21, v21, v36
	v_mul_f32_e32 v20, v20, v20
	v_mul_f32_e32 v22, v22, v22
	v_mul_f32_e32 v21, v21, v21
	v_cvt_pk_bf16_f32 v18, v22, v18
	v_cvt_pk_bf16_f32 v19, v19, v20
	v_cvt_pk_bf16_f32 v20, v26, v23
	v_cvt_pk_bf16_f32 v21, v24, v21
	global_store_dwordx4 v[34:35], v[18:21], off offset:256 nt
	ds_read_b32 v20, v148 offset:704
	v_max_f32_e32 v10, v10, v10
	v_max_f32_e32 v10, 0, v10
	v_max_f32_e32 v11, v11, v11
	v_max_f32_e32 v12, v12, v12
	s_waitcnt lgkmcnt(0)
	v_mul_f32_e32 v10, v10, v20
	v_max_f32_e32 v11, 0, v11
	v_max_f32_e32 v12, 0, v12
	v_max_f32_e32 v14, v14, v14
	v_mul_f32_e32 v21, v10, v10
	v_max_f32_e32 v10, v15, v15
	v_mul_f32_e32 v11, v11, v20
	v_mul_f32_e32 v12, v12, v20
	v_max_f32_e32 v14, 0, v14
	v_max_f32_e32 v10, 0, v10
	v_mul_f32_e32 v15, v11, v11
	v_max_f32_e32 v11, v16, v16
	v_mul_f32_e32 v16, v12, v12
	v_max_f32_e32 v12, v17, v17
	s_mov_b64 s[4:5], 0x2c0000
	v_mul_f32_e32 v14, v14, v20
	v_mul_f32_e32 v10, v10, v20
	v_max_f32_e32 v11, 0, v11
	v_max_f32_e32 v12, 0, v12
	v_max_f32_e32 v13, v13, v13
	v_lshl_add_u64 v[18:19], v[140:141], 0, s[4:5]
	v_mul_f32_e32 v14, v14, v14
	v_mul_f32_e32 v10, v10, v10
	v_mul_f32_e32 v11, v11, v20
	v_mul_f32_e32 v12, v12, v20
	v_max_f32_e32 v13, 0, v13
	s_mov_b32 s4, 0x2c0000
	v_max_f32_e32 v2, v2, v2
	v_max_f32_e32 v3, v3, v3
	v_max_f32_e32 v4, v4, v4
	v_mul_f32_e32 v11, v11, v11
	v_mul_f32_e32 v13, v13, v20
	v_mul_f32_e32 v12, v12, v12
	v_cvt_pk_bf16_f32 v10, v14, v10
	v_add_co_u32_e32 v14, vcc, s4, v140
	v_max_f32_e32 v2, 0, v2
	v_max_f32_e32 v3, 0, v3
	v_max_f32_e32 v4, 0, v4
	v_mul_f32_e32 v13, v13, v13
	v_cvt_pk_bf16_f32 v11, v11, v12
	v_cvt_pk_bf16_f32 v12, v21, v15
	v_addc_co_u32_e32 v15, vcc, 0, v141, vcc
	v_mul_f32_e32 v2, v2, v20
	v_mul_f32_e32 v3, v3, v20
	v_mul_f32_e32 v4, v4, v20
	v_cvt_pk_bf16_f32 v13, v16, v13
	global_store_dwordx4 v[14:15], v[10:13], off nt
	v_max_f32_e32 v5, v5, v5
	v_max_f32_e32 v6, v6, v6
	v_mul_f32_e32 v10, v2, v2
	v_max_f32_e32 v2, v7, v7
	v_mul_f32_e32 v7, v3, v3
	v_max_f32_e32 v3, v8, v8
	v_mul_f32_e32 v8, v4, v4
	v_max_f32_e32 v4, v9, v9
	v_max_f32_e32 v2, 0, v2
	v_max_f32_e32 v3, 0, v3
	v_max_f32_e32 v4, 0, v4
	v_max_f32_e32 v5, 0, v5
	v_max_f32_e32 v6, 0, v6
	v_mul_f32_e32 v2, v2, v20
	v_mul_f32_e32 v3, v3, v20
	v_mul_f32_e32 v4, v4, v20
	v_mul_f32_e32 v5, v5, v20
	v_mul_f32_e32 v6, v6, v20
	v_mul_f32_e32 v2, v2, v2
	v_mul_f32_e32 v3, v3, v3
	v_mul_f32_e32 v4, v4, v4
	v_mul_f32_e32 v5, v5, v5
	s_mov_b64 s[4:5], -1
	s_andn2_b64 vcc, exec, s[40:41]
	v_mul_f32_e32 v6, v6, v6
	v_cvt_pk_bf16_f32 v2, v6, v2
	v_cvt_pk_bf16_f32 v3, v3, v4
	v_cvt_pk_bf16_f32 v4, v10, v7
	v_cvt_pk_bf16_f32 v5, v8, v5
	global_store_dwordx4 v[18:19], v[2:5], off offset:256 nt
	s_cbranch_vccnz .LBB0_1329
	s_andn2_b64 vcc, exec, s[2:3]
	s_cbranch_vccnz .LBB0_1328
	s_barrier
	s_branch .LBB0_1328
